# combined: permlane row sums + write-back K/V stores + counted P5 tile-seam waits on top of the P4/P6 epilogue work
# baseline (speedup 1.0000x reference)
; #define LAS __attribute__((address_space(3)))
; #define MFMA16(a, b, c) __builtin_amdgcn_mfma_f32_16x16x32_bf16((a), (b), (c), 0, 0, 0)
; __device__ __forceinline__ void qkv_head_unit(const Params& p, LAS unsigned char* lds, int h, int blk_begin, int blk_end) {
;     ...
;         for (int pb = blk_begin + 2 * w; pb < blk_end; pb += 16) {
;             const bool two = (pb + 1) < blk_end;
;             const int blk1 = two ? pb + 1 : pb;
;             const int rowm[2] = {16 * pb + fr, 16 * blk1 + fr};
;             bf16x8 af[2][8]; float ssv[2]; u32x2 k1v[2], k2v[2];
; #pragma unroll
;             for (int m = 0; m < 2; ++m) { ssv[m] = ss_ckv[rowm[m]]; k1v[m] = *(const u32x2*)(P + (size_t)rowm[m] * INP + C_KR + 4 * fq); k2v[m] = *(const u32x2*)(P + (size_t)rowm[m] * INP + C_KR + 16 + 4 * fq);
; #pragma unroll
;                 for (int ks = 0; ks < 8; ++ks) af[m][ks] = *(const bf16x8*)(P + (size_t)rowm[m] * INP + C_CKV + 32 * ks + 8 * fq); }
;             {
;                 f32x4 acc[2][4];
; #pragma unroll
;                 for (int m = 0; m < 2; ++m)
; #pragma unroll
;                     for (int n = 0; n < 4; ++n) acc[m][n] = (f32x4){0.f, 0.f, 0.f, 0.f};
; #pragma unroll
;                 for (int ks = 0; ks < 8; ++ks)
; #pragma unroll
;                     for (int n = 0; n < 4; ++n) { const bf16x8 bw = *(const LAS bf16x8*)(wl + (16 * n + fr) * WKS + 32 * ks + 8 * fq);
;                         acc[0][n] = MFMA16(bw, af[0][ks], acc[0][n]); acc[1][n] = MFMA16(bw, af[1][ks], acc[1][n]); }
.LBB0_524:
	v_add_u32_e32 v177, 1, v159
	v_cmp_gt_i32_e32 vcc, s12, v177
	v_add_u32_e32 v126, v158, v161
	v_ashrrev_i32_e32 v127, 31, v126
	v_cndmask_b32_e32 v0, v159, v177, vcc
	v_lshlrev_b32_e32 v178, 4, v0
	v_or_b32_e32 v120, v178, v158
	v_lshl_add_u64 v[22:23], v[126:127], 2, s[42:43]
	v_mov_b64_e32 v[26:27], s[40:41]
	global_load_dword v127, v[22:23], off
	v_mad_i64_i32 v[22:23], s[4:5], v126, s89, v[26:27]
	v_lshlrev_b32_e32 v0, 1, v115
	v_ashrrev_i32_e32 v121, 31, v120
	v_lshl_add_u64 v[24:25], v[22:23], 0, v[0:1]
	v_lshl_add_u64 v[34:35], v[120:121], 2, s[42:43]
	v_mad_i64_i32 v[22:23], s[4:5], v120, s89, v[26:27]
	global_load_dwordx2 v[130:131], v[24:25], off offset:1280
	global_load_dwordx2 v[128:129], v[24:25], off offset:1312
	global_load_dword v121, v[34:35], off
	v_lshl_add_u64 v[34:35], v[22:23], 0, v[0:1]
	v_and_b32_e32 v0, 3, v163
	v_bfe_u32 v226, v163, 2, 4
	global_load_dwordx2 v[124:125], v[34:35], off offset:1280
	global_load_dwordx2 v[122:123], v[34:35], off offset:1312
	v_lshlrev_b32_e32 v0, 4, v0
	v_and_b32_e32 v227, -16, v126
	v_lshl_add_u64 v[28:29], v[26:27], 0, v[0:1]
	v_add_u32_e32 v227, v227, v226
	v_add_u32_e32 v226, v178, v226
	v_mad_i64_i32 v[22:23], s[4:5], v227, s89, v[28:29]
	v_mad_i64_i32 v[26:27], s[4:5], v226, s89, v[28:29]
	global_load_dwordx4 v[78:81], v[22:23], off offset:768
	global_load_dwordx4 v[82:85], v[26:27], off offset:768
	global_load_dwordx4 v[66:69], v[22:23], off offset:832
	global_load_dwordx4 v[74:77], v[26:27], off offset:832
	global_load_dwordx4 v[62:65], v[22:23], off offset:896
	global_load_dwordx4 v[70:73], v[26:27], off offset:896
	global_load_dwordx4 v[50:53], v[22:23], off offset:960
	global_load_dwordx4 v[58:61], v[26:27], off offset:960
	global_load_dwordx4 v[46:49], v[22:23], off offset:1024
	global_load_dwordx4 v[54:57], v[26:27], off offset:1024
	global_load_dwordx4 v[38:41], v[22:23], off offset:1088
	global_load_dwordx4 v[42:45], v[26:27], off offset:1088
	global_load_dwordx4 v[30:33], v[22:23], off offset:1152
	global_load_dwordx4 v[34:37], v[26:27], off offset:1152
	s_nop 0
	global_load_dwordx4 v[22:25], v[22:23], off offset:1216
	global_load_dwordx4 v[26:29], v[26:27], off offset:1216
	s_waitcnt vmcnt(15)
	ds_write_b128 v242, v[78:81]
	ds_read_b128 v[78:81], v243
	s_waitcnt vmcnt(14)
	ds_write_b128 v242, v[82:85] offset:1024
	ds_read_b128 v[82:85], v243 offset:1024
	s_waitcnt vmcnt(13)
	ds_write_b128 v242, v[66:69] offset:2048
	ds_read_b128 v[66:69], v243 offset:2048
	s_waitcnt vmcnt(12)
	ds_write_b128 v242, v[74:77]
	ds_read_b128 v[74:77], v243
	ds_read_b128 v[230:233], v164 offset:0
	ds_read_b128 v[234:237], v164 offset:8448
	ds_read_b128 v[238:241], v164 offset:16896
	ds_read_b128 v[180:183], v164 offset:25344
	s_waitcnt lgkmcnt(3)
	v_mfma_f32_16x16x32_bf16 v[188:191], v[230:233], v[78:81], 0
	v_fmamk_f32 v0, v127, 0x3b800000, v140
	v_rsq_f32_e32 v0, v0
	v_mfma_f32_16x16x32_bf16 v[98:101], v[230:233], v[82:85], 0
	ds_read_b128 v[230:233], v164 offset:64
	s_waitcnt lgkmcnt(3)
	v_mfma_f32_16x16x32_bf16 v[192:195], v[234:237], v[78:81], 0
	v_mfma_f32_16x16x32_bf16 v[86:89], v[234:237], v[82:85], 0
	ds_read_b128 v[234:237], v164 offset:8512
	s_waitcnt vmcnt(11)
	ds_write_b128 v242, v[62:65] offset:1024
	ds_read_b128 v[62:65], v243 offset:1024
	s_waitcnt vmcnt(10)
	ds_write_b128 v242, v[70:73] offset:2048
	ds_read_b128 v[70:73], v243 offset:2048
	s_waitcnt lgkmcnt(7)
	v_mfma_f32_16x16x32_bf16 v[196:199], v[238:241], v[78:81], 0
	v_mfma_f32_16x16x32_bf16 v[94:97], v[238:241], v[82:85], 0
	ds_read_b128 v[238:241], v164 offset:16960
	s_waitcnt lgkmcnt(7)
	v_mfma_f32_16x16x32_bf16 v[184:187], v[180:183], v[78:81], 0
	v_mfma_f32_16x16x32_bf16 v[90:93], v[180:183], v[82:85], 0
	ds_read_b128 v[180:183], v164 offset:25408
	s_waitcnt lgkmcnt(7)
	v_mfma_f32_16x16x32_bf16 v[188:191], v[230:233], v[66:69], v[188:191]
	v_mfma_f32_16x16x32_bf16 v[98:101], v[230:233], v[74:77], v[98:101]
	ds_read_b128 v[230:233], v164 offset:128
	s_waitcnt lgkmcnt(7)
	v_mfma_f32_16x16x32_bf16 v[192:195], v[234:237], v[66:69], v[192:195]
	v_mfma_f32_16x16x32_bf16 v[86:89], v[234:237], v[74:77], v[86:89]
	ds_read_b128 v[234:237], v164 offset:8576
	s_waitcnt vmcnt(9)
	ds_write_b128 v242, v[50:53]
	ds_read_b128 v[50:53], v243
	s_waitcnt vmcnt(8)
	ds_write_b128 v242, v[58:61] offset:1024
	ds_read_b128 v[58:61], v243 offset:1024
	s_waitcnt lgkmcnt(7)
	v_mfma_f32_16x16x32_bf16 v[196:199], v[238:241], v[66:69], v[196:199]
	v_mfma_f32_16x16x32_bf16 v[94:97], v[238:241], v[74:77], v[94:97]
	ds_read_b128 v[238:241], v164 offset:17024
	s_waitcnt lgkmcnt(7)
	v_mfma_f32_16x16x32_bf16 v[184:187], v[180:183], v[66:69], v[184:187]
	v_mfma_f32_16x16x32_bf16 v[90:93], v[180:183], v[74:77], v[90:93]
	ds_read_b128 v[180:183], v164 offset:25472
	s_waitcnt lgkmcnt(7)
	v_mfma_f32_16x16x32_bf16 v[188:191], v[230:233], v[62:65], v[188:191]
	v_mfma_f32_16x16x32_bf16 v[98:101], v[230:233], v[70:73], v[98:101]
	ds_read_b128 v[230:233], v164 offset:192
	s_waitcnt lgkmcnt(7)
	v_mfma_f32_16x16x32_bf16 v[192:195], v[234:237], v[62:65], v[192:195]
	v_mfma_f32_16x16x32_bf16 v[86:89], v[234:237], v[70:73], v[86:89]
	ds_read_b128 v[234:237], v164 offset:8640
	s_waitcnt vmcnt(7)
	ds_write_b128 v242, v[46:49] offset:2048
	ds_read_b128 v[46:49], v243 offset:2048
	s_waitcnt vmcnt(6)
	ds_write_b128 v242, v[54:57]
	ds_read_b128 v[54:57], v243
	s_waitcnt lgkmcnt(7)
	v_mfma_f32_16x16x32_bf16 v[196:199], v[238:241], v[62:65], v[196:199]
	v_mfma_f32_16x16x32_bf16 v[94:97], v[238:241], v[70:73], v[94:97]
	ds_read_b128 v[238:241], v164 offset:17088
	s_waitcnt lgkmcnt(7)
; #define LAS __attribute__((address_space(3)))
; #define MFMA16(a, b, c) __builtin_amdgcn_mfma_f32_16x16x32_bf16((a), (b), (c), 0, 0, 0)
; __device__ __forceinline__ void qkv_head_unit(const Params& p, LAS unsigned char* lds, int h, int blk_begin, int blk_end) {
;     ...
; #pragma unroll
;                 for (int ks = 0; ks < 8; ++ks)
; #pragma unroll
;                     for (int n = 0; n < 4; ++n) { const bf16x8 bw = *(const LAS bf16x8*)(wl + (16 * n + fr) * WKS + 32 * ks + 8 * fq);
;                         acc[0][n] = MFMA16(bw, af[0][ks], acc[0][n]); acc[1][n] = MFMA16(bw, af[1][ks], acc[1][n]); }
	v_mfma_f32_16x16x32_bf16 v[184:187], v[180:183], v[62:65], v[184:187]
	v_mfma_f32_16x16x32_bf16 v[90:93], v[180:183], v[70:73], v[90:93]
	ds_read_b128 v[180:183], v164 offset:25536
	s_waitcnt lgkmcnt(7)
	v_mfma_f32_16x16x32_bf16 v[188:191], v[230:233], v[50:53], v[188:191]
	v_mfma_f32_16x16x32_bf16 v[98:101], v[230:233], v[58:61], v[98:101]
	ds_read_b128 v[230:233], v164 offset:256
	s_waitcnt lgkmcnt(7)
	v_mfma_f32_16x16x32_bf16 v[192:195], v[234:237], v[50:53], v[192:195]
	v_mfma_f32_16x16x32_bf16 v[86:89], v[234:237], v[58:61], v[86:89]
	ds_read_b128 v[234:237], v164 offset:8704
	s_waitcnt vmcnt(5)
	ds_write_b128 v242, v[38:41] offset:1024
	ds_read_b128 v[38:41], v243 offset:1024
	s_waitcnt vmcnt(4)
	ds_write_b128 v242, v[42:45] offset:2048
	ds_read_b128 v[42:45], v243 offset:2048
	s_waitcnt lgkmcnt(7)
	v_mfma_f32_16x16x32_bf16 v[196:199], v[238:241], v[50:53], v[196:199]
	v_mfma_f32_16x16x32_bf16 v[94:97], v[238:241], v[58:61], v[94:97]
	ds_read_b128 v[238:241], v164 offset:17152
	s_waitcnt lgkmcnt(7)
	v_mfma_f32_16x16x32_bf16 v[184:187], v[180:183], v[50:53], v[184:187]
	v_mfma_f32_16x16x32_bf16 v[90:93], v[180:183], v[58:61], v[90:93]
	ds_read_b128 v[180:183], v164 offset:25600
	s_waitcnt lgkmcnt(7)
	v_mfma_f32_16x16x32_bf16 v[188:191], v[230:233], v[46:49], v[188:191]
	v_mfma_f32_16x16x32_bf16 v[98:101], v[230:233], v[54:57], v[98:101]
	ds_read_b128 v[230:233], v164 offset:320
	s_waitcnt lgkmcnt(7)
	v_mfma_f32_16x16x32_bf16 v[192:195], v[234:237], v[46:49], v[192:195]
	v_mfma_f32_16x16x32_bf16 v[86:89], v[234:237], v[54:57], v[86:89]
	ds_read_b128 v[234:237], v164 offset:8768
	s_waitcnt vmcnt(3)
	ds_write_b128 v242, v[30:33]
	ds_read_b128 v[30:33], v243
	s_waitcnt vmcnt(2)
	ds_write_b128 v242, v[34:37] offset:1024
	ds_read_b128 v[34:37], v243 offset:1024
	s_waitcnt lgkmcnt(7)
	v_mfma_f32_16x16x32_bf16 v[196:199], v[238:241], v[46:49], v[196:199]
	v_mfma_f32_16x16x32_bf16 v[94:97], v[238:241], v[54:57], v[94:97]
	ds_read_b128 v[238:241], v164 offset:17216
	s_waitcnt lgkmcnt(7)
	v_mfma_f32_16x16x32_bf16 v[184:187], v[180:183], v[46:49], v[184:187]
	v_mfma_f32_16x16x32_bf16 v[90:93], v[180:183], v[54:57], v[90:93]
	ds_read_b128 v[180:183], v164 offset:25664
	s_waitcnt lgkmcnt(7)
	v_mfma_f32_16x16x32_bf16 v[188:191], v[230:233], v[38:41], v[188:191]
	v_mfma_f32_16x16x32_bf16 v[98:101], v[230:233], v[42:45], v[98:101]
	ds_read_b128 v[230:233], v164 offset:384
	s_waitcnt lgkmcnt(7)
	v_mfma_f32_16x16x32_bf16 v[192:195], v[234:237], v[38:41], v[192:195]
	v_mfma_f32_16x16x32_bf16 v[86:89], v[234:237], v[42:45], v[86:89]
	ds_read_b128 v[234:237], v164 offset:8832
	s_waitcnt vmcnt(1)
	ds_write_b128 v242, v[22:25] offset:2048
	ds_read_b128 v[22:25], v243 offset:2048
	s_waitcnt vmcnt(0)
	ds_write_b128 v242, v[26:29]
	ds_read_b128 v[26:29], v243
	s_waitcnt lgkmcnt(7)
	v_mfma_f32_16x16x32_bf16 v[196:199], v[238:241], v[38:41], v[196:199]
	v_mfma_f32_16x16x32_bf16 v[94:97], v[238:241], v[42:45], v[94:97]
	ds_read_b128 v[238:241], v164 offset:17280
	s_waitcnt lgkmcnt(7)
	v_mfma_f32_16x16x32_bf16 v[184:187], v[180:183], v[38:41], v[184:187]
	v_mfma_f32_16x16x32_bf16 v[90:93], v[180:183], v[42:45], v[90:93]
	ds_read_b128 v[180:183], v164 offset:25728
	s_waitcnt lgkmcnt(7)
	v_mfma_f32_16x16x32_bf16 v[188:191], v[230:233], v[30:33], v[188:191]
	v_mfma_f32_16x16x32_bf16 v[98:101], v[230:233], v[34:37], v[98:101]
	ds_read_b128 v[230:233], v164 offset:448
	s_waitcnt lgkmcnt(7)
	v_mfma_f32_16x16x32_bf16 v[192:195], v[234:237], v[30:33], v[192:195]
	v_mfma_f32_16x16x32_bf16 v[86:89], v[234:237], v[34:37], v[86:89]
	ds_read_b128 v[234:237], v164 offset:8896
	s_waitcnt lgkmcnt(3)
	v_mfma_f32_16x16x32_bf16 v[196:199], v[238:241], v[30:33], v[196:199]
	v_mfma_f32_16x16x32_bf16 v[94:97], v[238:241], v[34:37], v[94:97]
	ds_read_b128 v[238:241], v164 offset:17344
	s_waitcnt lgkmcnt(3)
	v_mfma_f32_16x16x32_bf16 v[184:187], v[180:183], v[30:33], v[184:187]
	v_mfma_f32_16x16x32_bf16 v[90:93], v[180:183], v[34:37], v[90:93]
	ds_read_b128 v[180:183], v164 offset:25792
	s_waitcnt lgkmcnt(3)
	v_mfma_f32_16x16x32_bf16 v[188:191], v[230:233], v[22:25], v[188:191]
	v_mfma_f32_16x16x32_bf16 v[98:101], v[230:233], v[26:29], v[98:101]
	s_waitcnt lgkmcnt(2)
	v_mfma_f32_16x16x32_bf16 v[192:195], v[234:237], v[22:25], v[192:195]
	v_mfma_f32_16x16x32_bf16 v[86:89], v[234:237], v[26:29], v[86:89]
	s_waitcnt lgkmcnt(1)
	v_mfma_f32_16x16x32_bf16 v[196:199], v[238:241], v[22:25], v[196:199]
	v_mfma_f32_16x16x32_bf16 v[94:97], v[238:241], v[26:29], v[94:97]
	s_waitcnt lgkmcnt(0)
; #define LAS __attribute__((address_space(3)))
; __device__ __forceinline__ unsigned cvt_pk(float lo, float hi) { unsigned r; asm("v_cvt_pk_bf16_f32 %0, %1, %2" : "=v"(r) : "v"(lo), "v"(hi)); return r; }
; __device__ __forceinline__ float bflo(unsigned w) { return __uint_as_float(w << 16); }
; __device__ __forceinline__ float bfhi(unsigned w) { return __uint_as_float(w & 0xffff0000u); }
; __device__ __forceinline__ float frsq(float x) { return __builtin_amdgcn_rsqf(x); }
; __device__ __forceinline__ void qkv_head_unit(const Params& p, LAS unsigned char* lds, int h, int blk_begin, int blk_end) {
;     ...
;                 for (int mi = 0; mi < 2; ++mi) {
;                     const bool valid = (mi == 0) || two;
;                     const int t = rowm[mi] % TT;
;                     const float sc = frsq(ssv[mi] * (1.0f / 256.0f) + EPS);
;                     const u32x2 k1 = k1v[mi], k2 = k2v[mi];
;                     f32x4 kr1 = (f32x4){bflo(k1.x), bfhi(k1.x), bflo(k1.y), bfhi(k1.y)}, kr2 = (f32x4){bflo(k2.x), bfhi(k2.x), bflo(k2.y), bfhi(k2.y)};
;                     float ssq = (kr1[0] * kr1[0] + kr1[1] * kr1[1]) + (kr1[2] * kr1[2] + kr1[3] * kr1[3]) + (kr2[0] * kr2[0] + kr2[1] * kr2[1]) + (kr2[2] * kr2[2] + kr2[3] * kr2[3]);
; #pragma unroll
;                     for (int n = 0; n < 4; ++n) { acc[mi][n] *= sc; ssq += (acc[mi][n][0] * acc[mi][n][0] + acc[mi][n][1] * acc[mi][n][1]) + (acc[mi][n][2] * acc[mi][n][2] + acc[mi][n][3] * acc[mi][n][3]); }
;                     ssq += __shfl_xor(ssq, 16); ssq += __shfl_xor(ssq, 32);
;                     const float rk = frsq(ssq * (1.0f / 96.0f) + EPS);
;                     LAS bf16_t* dstk = stg + fr * 104 + 4 * fq;
; #pragma unroll
;                     for (int n = 0; n < 4; ++n) { const f32x4 v = acc[mi][n] * rk * gvv[n]; u32x2 wv; wv.x = cvt_pk(v[0], v[1]); wv.y = cvt_pk(v[2], v[3]); *(LAS u32x2*)(dstk + 16 * n) = wv; }
;                     { kr1 = kr1 * rk * gvv[4]; kr2 = kr2 * rk * gvv[5];
	v_mfma_f32_16x16x32_bf16 v[184:187], v[180:183], v[22:25], v[184:187]
	v_mfma_f32_16x16x32_bf16 v[90:93], v[180:183], v[26:29], v[90:93]
	v_lshlrev_b32_e32 v137, 16, v131
	v_lshlrev_b32_e32 v136, 16, v130
	v_and_b32_e32 v131, 0xffff0000, v131
	v_and_b32_e32 v130, 0xffff0000, v130
	v_pk_mul_f32 v[138:139], v[130:131], v[130:131]
	v_lshlrev_b32_e32 v132, 16, v129
	v_and_b32_e32 v134, 0xffff0000, v129
	s_nop 7
	v_pk_mul_f32 v[196:197], v[0:1], v[196:197] op_sel_hi:[0,1]
	v_mul_f32_e64 v184, v0, v184
	v_mul_f32_e64 v185, v0, v185
	v_pk_mul_f32 v[186:187], v[0:1], v[186:187] op_sel_hi:[0,1]
	v_pk_fma_f32 v[180:181], v[136:137], v[136:137], v[138:139]
	v_and_b32_e32 v139, 0xffff0000, v128
	v_lshlrev_b32_e32 v138, 16, v128
	v_pk_mul_f32 v[128:129], v[0:1], v[190:191] op_sel_hi:[0,1]
	v_pk_mul_f32 v[182:183], v[0:1], v[188:189] op_sel_hi:[0,1]
	v_mul_f32_e32 v190, v139, v139
	v_mul_f32_e32 v127, v128, v128
	v_mul_f32_e32 v179, v129, v129
	v_mov_b32_e32 v135, v183
	v_pk_add_f32 v[180:181], v[180:181], v[180:181] op_sel:[0,1] op_sel_hi:[1,0]
	v_pk_fma_f32 v[190:191], v[138:139], v[138:139], v[190:191] op_sel_hi:[1,1,0]
	v_mov_b32_e32 v133, v182
	v_pk_mul_f32 v[188:189], v[134:135], v[134:135]
	v_mov_b32_e32 v181, v127
	v_mov_b32_e32 v191, v179
	v_pk_fma_f32 v[188:189], v[132:133], v[132:133], v[188:189]
	v_pk_add_f32 v[180:181], v[180:181], v[190:191]
	v_pk_mul_f32 v[190:191], v[0:1], v[192:193] op_sel_hi:[0,1]
	v_pk_add_f32 v[180:181], v[188:189], v[180:181]
	v_pk_mul_f32 v[188:189], v[0:1], v[194:195] op_sel_hi:[0,1]
	v_pk_mul_f32 v[192:193], v[188:189], v[188:189]
	v_pk_mul_f32 v[194:195], v[190:191], v[190:191]
	v_mul_f32_e32 v127, v184, v184
	v_pk_mov_b32 v[200:201], v[194:195], v[192:193] op_sel:[1,0]
	v_mov_b32_e32 v195, v193
	v_pk_add_f32 v[192:193], v[200:201], v[194:195]
	v_mul_f32_e32 v133, v185, v185
	v_pk_add_f32 v[180:181], v[180:181], v[180:181] op_sel:[0,1] op_sel_hi:[1,0]
	v_pk_add_f32 v[192:193], v[192:193], v[192:193] op_sel:[0,1] op_sel_hi:[1,0]
	v_pk_mul_f32 v[194:195], v[0:1], v[198:199] op_sel_hi:[0,1]
	v_mov_b32_e32 v181, v127
	v_mov_b32_e32 v193, v133
	v_pk_add_f32 v[180:181], v[180:181], v[192:193]
	v_mul_f32_e32 v192, v197, v197
	v_mul_f32_e32 v198, v195, v195
	v_mul_f32_e32 v135, v186, v186
	v_mul_f32_e32 v179, v187, v187
	v_pk_fma_f32 v[192:193], v[196:197], v[196:197], v[192:193] op_sel_hi:[1,1,0]
	v_pk_fma_f32 v[198:199], v[194:195], v[194:195], v[198:199] op_sel_hi:[1,1,0]
	v_mov_b32_e32 v193, v135
	v_mov_b32_e32 v199, v179
	v_pk_add_f32 v[192:193], v[192:193], v[198:199]
	s_nop 0
	v_pk_add_f32 v[180:181], v[180:181], v[192:193]
	s_nop 0
	v_add_f32_e32 v127, v180, v181
	v_mov_b32_e32 v133, v127
	s_nop 1
	v_permlane16_swap_b32_e32 v127, v133
	s_waitcnt lgkmcnt(0)
	v_add_f32_e32 v127, v127, v133
	v_mov_b32_e32 v133, v127
	s_nop 1
	v_permlane32_swap_b32_e32 v127, v133
	s_waitcnt lgkmcnt(0)
	v_add_f32_e32 v127, v127, v133
	v_fmamk_f32 v127, v127, 0x3c2aaaab, v140
	v_rsq_f32_e32 v180, v127
	v_add_u32_e32 v127, v160, v114
	v_mov_b32_e32 v133, v134
	v_pk_mul_f32 v[182:183], v[182:183], v[180:181] op_sel_hi:[1,0]
	v_pk_mul_f32 v[128:129], v[128:129], v[180:181] op_sel_hi:[1,0]
	v_pk_mul_f32 v[182:183], v[6:7], v[182:183]
	v_pk_mul_f32 v[128:129], v[8:9], v[128:129]
	v_cvt_pk_bf16_f32 v182, v182, v183
	v_pk_mul_f32 v[188:189], v[188:189], v[180:181] op_sel_hi:[1,0]
	v_cvt_pk_bf16_f32 v183, v128, v129
	v_pk_mul_f32 v[128:129], v[190:191], v[180:181] op_sel_hi:[1,0]
	v_pk_mul_f32 v[188:189], v[12:13], v[188:189]
	v_pk_mul_f32 v[128:129], v[10:11], v[128:129]
	v_pk_mul_f32 v[134:135], v[138:139], v[180:181] op_sel_hi:[1,0]
	v_cvt_pk_bf16_f32 v128, v128, v129
	v_cvt_pk_bf16_f32 v129, v188, v189
	ds_write2_b64 v127, v[182:183], v[128:129] offset1:4
	v_pk_mul_f32 v[128:129], v[196:197], v[180:181] op_sel_hi:[1,0]
	v_pk_mul_f32 v[182:183], v[194:195], v[180:181] op_sel_hi:[1,0]
	v_pk_mul_f32 v[128:129], v[14:15], v[128:129]
	v_pk_mul_f32 v[182:183], v[16:17], v[182:183]
	v_cvt_pk_bf16_f32 v128, v128, v129
	v_mov_b32_e32 v139, v134
	v_cvt_pk_bf16_f32 v129, v182, v183
	v_pk_mul_f32 v[182:183], v[184:185], v[180:181] op_sel_hi:[1,0]
	v_pk_mul_f32 v[184:185], v[186:187], v[180:181] op_sel_hi:[1,0]
	v_pk_mul_f32 v[182:183], v[18:19], v[182:183]
	v_pk_mul_f32 v[184:185], v[20:21], v[184:185]
	v_cvt_pk_bf16_f32 v182, v182, v183
	v_pk_mul_f32 v[132:133], v[132:133], v[180:181] op_sel_hi:[1,0]
	v_cvt_pk_bf16_f32 v183, v184, v185
	ds_write2_b64 v127, v[128:129], v[182:183] offset0:8 offset1:12
	v_mul_hi_i32 v128, v126, s90
	v_lshrrev_b32_e32 v129, 31, v128
	v_ashrrev_i32_e32 v128, 7, v128
	v_add_u32_e32 v128, v128, v129
	v_mul_lo_u32 v128, v128, s86
	v_sub_u32_e32 v126, v126, v128
	v_cvt_f32_i32_e32 v126, v126
	v_mov_b32_e32 v128, v137
	v_mov_b32_e32 v137, v130
	v_mov_b32_e32 v129, v131
	v_pk_mul_f32 v[130:131], v[180:181], v[136:137] op_sel_hi:[0,1]
	v_mul_f32_e32 v136, v154, v126
	v_mul_f32_e32 v137, 0.15915494, v136
	v_rndne_f32_e32 v137, v137
	v_fmac_f32_e32 v136, 0xc0c90fdb, v137
	v_fmac_f32_e32 v136, 0x343bbd2e, v137
	v_mul_f32_e32 v136, 0.15915494, v136
	v_sin_f32_e32 v137, v136
	v_cos_f32_e32 v136, v136
	v_mov_b32_e32 v138, v130
	v_mul_f32_e32 v130, v155, v126
	v_mul_f32_e32 v134, 0.15915494, v130
	v_pk_mul_f32 v[138:139], v[118:119], v[138:139]
	v_rndne_f32_e32 v134, v134
	v_pk_mul_f32 v[128:129], v[180:181], v[128:129] op_sel_hi:[0,1]
	v_pk_mul_f32 v[180:181], v[136:137], v[138:139]
	v_fmac_f32_e32 v130, 0xc0c90fdb, v134
	v_sub_f32_e32 v179, v180, v181
	v_mov_b32_e32 v180, v137
	v_mov_b32_e32 v181, v136
	v_fmac_f32_e32 v130, 0x343bbd2e, v134
	v_pk_mul_f32 v[136:137], v[180:181], v[138:139]
	v_mul_f32_e32 v130, 0.15915494, v130
; #define LAS __attribute__((address_space(3)))
; __device__ __forceinline__ unsigned cvt_pk(float lo, float hi) { unsigned r; asm("v_cvt_pk_bf16_f32 %0, %1, %2" : "=v"(r) : "v"(lo), "v"(hi)); return r; }
; __device__ __forceinline__ void qkv_head_unit(const Params& p, LAS unsigned char* lds, int h, int blk_begin, int blk_end) {
;     ...
;                 for (int mi = 0; mi < 2; ++mi) {
;                     const bool valid = (mi == 0) || two;
;                     const int t = rowm[mi] % TT;
;                     const float sc = frsq(ssv[mi] * (1.0f / 256.0f) + EPS);
;                     const u32x2 k1 = k1v[mi], k2 = k2v[mi];
;                     f32x4 kr1 = (f32x4){bflo(k1.x), bfhi(k1.x), bflo(k1.y), bfhi(k1.y)}, kr2 = (f32x4){bflo(k2.x), bfhi(k2.x), bflo(k2.y), bfhi(k2.y)};
;                     float ssq = (kr1[0] * kr1[0] + kr1[1] * kr1[1]) + (kr1[2] * kr1[2] + kr1[3] * kr1[3]) + (kr2[0] * kr2[0] + kr2[1] * kr2[1]) + (kr2[2] * kr2[2] + kr2[3] * kr2[3]);
; #pragma unroll
;                     for (int n = 0; n < 4; ++n) { acc[mi][n] *= sc; ssq += (acc[mi][n][0] * acc[mi][n][0] + acc[mi][n][1] * acc[mi][n][1]) + (acc[mi][n][2] * acc[mi][n][2] + acc[mi][n][3] * acc[mi][n][3]); }
;                     ssq += __shfl_xor(ssq, 16); ssq += __shfl_xor(ssq, 32);
;     ...
;                     { kr1 = kr1 * rk * gvv[4]; kr2 = kr2 * rk * gvv[5];
;                       f32x4 o1, o2;
; #pragma unroll
;                       for (int i = 0; i < 4; ++i) { float sn, cs; sincos_rr((float)t * frq[i], sn, cs);
;                           o1[i] = kr1[i] * cs - kr2[i] * sn; o2[i] = kr1[i] * sn + kr2[i] * cs; }
;                       u32x2 wv; wv.x = cvt_pk(o1[0], o1[1]); wv.y = cvt_pk(o1[2], o1[3]); *(LAS u32x2*)(dstk + 64) = wv; wv.x = cvt_pk(o2[0], o2[1]); wv.y = cvt_pk(o2[2], o2[3]); *(LAS u32x2*)(dstk + 80) = wv; }
;                     asm volatile("s_waitcnt lgkmcnt(0)" ::: "memory");
; #pragma unroll
;                     for (int j = 0; j < 3; ++j) { const int c = lane + 64 * j, rw = c / 12, cc = c % 12; const int row2 = 16 * (mi ? blk1 : pb) + rw, b2 = row2 / TT, t2 = row2 % TT;
;                         const u32x4 v = *(const LAS u32x4*)(stg + rw * 104 + 8 * cc);
;                         if (valid) __builtin_nontemporal_store(v, (u32x4*)(Kb + (((size_t)(b2 * NH + h)) * TKP + t2) * QKH + 8 * cc)); }
	v_add_f32_e32 v138, v136, v137
	v_sin_f32_e32 v137, v130
	v_cos_f32_e32 v136, v130
	v_mov_b32_e32 v134, v131
	v_pk_mul_f32 v[130:131], v[2:3], v[134:135]
	s_nop 0
	v_pk_mul_f32 v[134:135], v[136:137], v[130:131]
	s_nop 0
	v_sub_f32_e32 v139, v134, v135
	v_mov_b32_e32 v134, v137
	v_mov_b32_e32 v135, v136
	v_pk_mul_f32 v[130:131], v[134:135], v[130:131]
	v_mov_b32_e32 v134, v128
	v_add_f32_e32 v180, v130, v131
	v_mul_f32_e32 v130, v156, v126
	v_mul_f32_e32 v131, 0.15915494, v130
	v_rndne_f32_e32 v131, v131
	v_fmac_f32_e32 v130, 0xc0c90fdb, v131
	v_fmac_f32_e32 v130, 0x343bbd2e, v131
	v_mul_f32_e32 v130, 0.15915494, v130
	v_sin_f32_e32 v131, v130
	v_cos_f32_e32 v130, v130
	v_mul_f32_e32 v126, v157, v126
	v_mov_b32_e32 v135, v132
	v_mul_f32_e32 v128, 0.15915494, v126
	v_pk_mul_f32 v[134:135], v[116:117], v[134:135]
	v_rndne_f32_e32 v128, v128
	v_pk_mul_f32 v[136:137], v[130:131], v[134:135]
	v_fmac_f32_e32 v126, 0xc0c90fdb, v128
	v_sub_f32_e32 v181, v136, v137
	v_mov_b32_e32 v136, v131
	v_mov_b32_e32 v137, v130
	v_fmac_f32_e32 v126, 0x343bbd2e, v128
	v_pk_mul_f32 v[130:131], v[136:137], v[134:135]
	v_mul_f32_e32 v126, 0.15915494, v126
	v_add_f32_e32 v134, v130, v131
	v_sin_f32_e32 v131, v126
	v_cos_f32_e32 v130, v126
	v_mov_b32_e32 v132, v129
	v_pk_mul_f32 v[128:129], v[4:5], v[132:133]
	s_nop 0
	v_pk_mul_f32 v[132:133], v[130:131], v[128:129]
	s_nop 0
	v_sub_f32_e32 v126, v132, v133
	v_mov_b32_e32 v132, v131
	v_mov_b32_e32 v133, v130
	v_pk_mul_f32 v[128:129], v[132:133], v[128:129]
	v_cvt_pk_bf16_f32 v130, v138, v180
	s_nop 0
	v_add_f32_e32 v131, v128, v129
	v_cvt_pk_bf16_f32 v129, v181, v126
	v_add_u32_e32 v126, v107, v161
	v_mul_hi_i32 v132, v126, s90
	v_lshrrev_b32_e32 v133, 31, v132
	v_ashrrev_i32_e32 v132, 7, v132
	v_add_u32_e32 v133, v132, v133
	v_mul_i32_i24_e32 v132, 0x810, v133
	v_sub_u32_e32 v132, v126, v132
	v_lshl_or_b32 v126, v133, 3, s16
	v_cvt_pk_bf16_f32 v131, v134, v131
	v_mul_hi_i32_i24_e32 v135, 0x840, v126
	v_mul_i32_i24_e32 v134, 0x840, v126
	v_ashrrev_i32_e32 v133, 31, v132
	v_lshl_add_u64 v[132:133], v[134:135], 0, v[132:133]
	v_mad_u64_u32 v[134:135], s[4:5], v132, s91, v[108:109]
	v_cvt_pk_bf16_f32 v128, v179, v139
	ds_write2_b64 v127, v[128:129], v[130:131] offset0:16 offset1:20
	v_mov_b32_e32 v126, v135
	s_waitcnt lgkmcnt(0)
	v_mad_u64_u32 v[132:133], s[4:5], v133, s91, v[126:127]
	v_add_u32_e32 v126, v170, v161
	ds_read_b128 v[128:131], v173
	v_mov_b32_e32 v135, v132
	v_mul_hi_i32 v132, v126, s90
	v_lshrrev_b32_e32 v133, 31, v132
	v_ashrrev_i32_e32 v132, 7, v132
	v_add_u32_e32 v133, v132, v133
	v_mul_i32_i24_e32 v132, 0x810, v133
	v_sub_u32_e32 v132, v126, v132
	v_lshl_or_b32 v126, v133, 3, s16
	s_waitcnt lgkmcnt(0)
	global_store_dwordx4 v[134:135], v[128:131], off
	v_mul_hi_i32_i24_e32 v135, 0x840, v126
	v_mul_i32_i24_e32 v134, 0x840, v126
	v_ashrrev_i32_e32 v133, 31, v132
	v_lshl_add_u64 v[132:133], v[134:135], 0, v[132:133]
	v_mad_u64_u32 v[134:135], s[4:5], v132, s91, v[110:111]
	v_mov_b32_e32 v126, v135
	v_mad_u64_u32 v[132:133], s[4:5], v133, s91, v[126:127]
	v_add_u32_e32 v126, v171, v161
	ds_read_b128 v[128:131], v174
	v_mov_b32_e32 v135, v132
	v_mul_hi_i32 v132, v126, s90
	v_lshrrev_b32_e32 v133, 31, v132
	v_ashrrev_i32_e32 v132, 7, v132
	v_add_u32_e32 v133, v132, v133
	v_mul_i32_i24_e32 v132, 0x810, v133
	v_sub_u32_e32 v132, v126, v132
	v_lshl_or_b32 v126, v133, 3, s16
	s_waitcnt lgkmcnt(0)
	global_store_dwordx4 v[134:135], v[128:131], off
	v_mul_hi_i32_i24_e32 v135, 0x840, v126
	v_mul_i32_i24_e32 v134, 0x840, v126
	v_ashrrev_i32_e32 v133, 31, v132
	ds_read_b128 v[128:131], v175
	v_lshl_add_u64 v[132:133], v[134:135], 0, v[132:133]
	v_mad_u64_u32 v[134:135], s[4:5], v132, s91, v[112:113]
	v_mov_b32_e32 v126, v135
	v_mad_u64_u32 v[132:133], s[4:5], v133, s91, v[126:127]
	v_mov_b32_e32 v135, v132
	s_waitcnt lgkmcnt(0)
	global_store_dwordx4 v[134:135], v[128:131], off
	s_waitcnt lgkmcnt(0)
	v_fmamk_f32 v121, v121, 0x3b800000, v140
	v_rsq_f32_e32 v126, v121
	v_lshlrev_b32_e32 v133, 16, v125
	v_lshlrev_b32_e32 v132, 16, v124
	v_and_b32_e32 v125, 0xffff0000, v125
	v_and_b32_e32 v124, 0xffff0000, v124
	v_pk_mul_f32 v[134:135], v[124:125], v[124:125]
	v_and_b32_e32 v137, 0xffff0000, v122
	v_pk_fma_f32 v[134:135], v[132:133], v[132:133], v[134:135]
	v_lshlrev_b32_e32 v136, 16, v122
	v_pk_mul_f32 v[98:99], v[126:127], v[98:99] op_sel_hi:[0,1]
	v_pk_mul_f32 v[100:101], v[126:127], v[100:101] op_sel_hi:[0,1]
	v_mul_f32_e32 v138, v137, v137
	v_and_b32_e32 v130, 0xffff0000, v123
	v_mul_f32_e32 v121, v100, v100
	v_mul_f32_e32 v179, v101, v101
	v_mov_b32_e32 v131, v99
	v_pk_add_f32 v[134:135], v[134:135], v[134:135] op_sel:[0,1] op_sel_hi:[1,0]
	v_pk_fma_f32 v[138:139], v[136:137], v[136:137], v[138:139] op_sel_hi:[1,1,0]
	v_lshlrev_b32_e32 v128, 16, v123
	v_mov_b32_e32 v129, v98
	v_pk_mul_f32 v[122:123], v[130:131], v[130:131]
	v_mov_b32_e32 v135, v121
	v_mov_b32_e32 v139, v179
	v_pk_fma_f32 v[122:123], v[128:129], v[128:129], v[122:123]
	v_pk_add_f32 v[134:135], v[134:135], v[138:139]
	v_pk_mul_f32 v[88:89], v[126:127], v[88:89] op_sel_hi:[0,1]
	v_pk_mul_f32 v[86:87], v[126:127], v[86:87] op_sel_hi:[0,1]
	v_pk_add_f32 v[122:123], v[122:123], v[134:135]
	v_pk_mul_f32 v[134:135], v[86:87], v[86:87]
	v_pk_mul_f32 v[138:139], v[88:89], v[88:89]
	v_pk_mul_f32 v[90:91], v[126:127], v[90:91] op_sel_hi:[0,1]
	v_pk_mov_b32 v[180:181], v[134:135], v[138:139] op_sel:[1,0]
	v_mov_b32_e32 v135, v139
	v_pk_add_f32 v[134:135], v[180:181], v[134:135]
	v_mul_f32_e32 v121, v90, v90
	v_mul_f32_e32 v129, v91, v91
	v_pk_add_f32 v[122:123], v[122:123], v[122:123] op_sel:[0,1] op_sel_hi:[1,0]
	v_pk_add_f32 v[134:135], v[134:135], v[134:135] op_sel:[0,1] op_sel_hi:[1,0]
	v_pk_mul_f32 v[96:97], v[126:127], v[96:97] op_sel_hi:[0,1]
	v_pk_mul_f32 v[94:95], v[126:127], v[94:95] op_sel_hi:[0,1]
	v_mov_b32_e32 v123, v121
	v_mov_b32_e32 v135, v129
	v_pk_mul_f32 v[92:93], v[126:127], v[92:93] op_sel_hi:[0,1]
	v_pk_add_f32 v[122:123], v[122:123], v[134:135]
	v_mul_f32_e32 v134, v95, v95
	v_mul_f32_e32 v138, v97, v97
	v_mul_f32_e32 v131, v92, v92
	v_mul_f32_e32 v179, v93, v93
	v_pk_fma_f32 v[134:135], v[94:95], v[94:95], v[134:135] op_sel_hi:[1,1,0]
	v_pk_fma_f32 v[138:139], v[96:97], v[96:97], v[138:139] op_sel_hi:[1,1,0]
	v_mov_b32_e32 v135, v131
	v_mov_b32_e32 v139, v179
	v_pk_add_f32 v[134:135], v[134:135], v[138:139]
	v_mov_b32_e32 v129, v130
	v_pk_add_f32 v[122:123], v[122:123], v[134:135]
	s_nop 0
	v_add_f32_e32 v121, v122, v123
	v_mov_b32_e32 v122, v121
	s_nop 1
	v_permlane16_swap_b32_e32 v121, v122
	s_waitcnt lgkmcnt(0)
; #define LAS __attribute__((address_space(3)))
; __device__ __forceinline__ unsigned cvt_pk(float lo, float hi) { unsigned r; asm("v_cvt_pk_bf16_f32 %0, %1, %2" : "=v"(r) : "v"(lo), "v"(hi)); return r; }
; __device__ __forceinline__ float frsq(float x) { return __builtin_amdgcn_rsqf(x); }
; __device__ __forceinline__ void qkv_head_unit(const Params& p, LAS unsigned char* lds, int h, int blk_begin, int blk_end) {
;     ...
;                     ssq += __shfl_xor(ssq, 16); ssq += __shfl_xor(ssq, 32);
;                     const float rk = frsq(ssq * (1.0f / 96.0f) + EPS);
;                     LAS bf16_t* dstk = stg + fr * 104 + 4 * fq;
; #pragma unroll
;                     for (int n = 0; n < 4; ++n) { const f32x4 v = acc[mi][n] * rk * gvv[n]; u32x2 wv; wv.x = cvt_pk(v[0], v[1]); wv.y = cvt_pk(v[2], v[3]); *(LAS u32x2*)(dstk + 16 * n) = wv; }
;                     { kr1 = kr1 * rk * gvv[4]; kr2 = kr2 * rk * gvv[5];
;                       f32x4 o1, o2;
; #pragma unroll
;                       for (int i = 0; i < 4; ++i) { float sn, cs; sincos_rr((float)t * frq[i], sn, cs);
;                           o1[i] = kr1[i] * cs - kr2[i] * sn; o2[i] = kr1[i] * sn + kr2[i] * cs; }
;                       u32x2 wv; wv.x = cvt_pk(o1[0], o1[1]); wv.y = cvt_pk(o1[2], o1[3]); *(LAS u32x2*)(dstk + 64) = wv; wv.x = cvt_pk(o2[0], o2[1]); wv.y = cvt_pk(o2[2], o2[3]); *(LAS u32x2*)(dstk + 80) = wv; }
;                     asm volatile("s_waitcnt lgkmcnt(0)" ::: "memory");
; #pragma unroll
;                     for (int j = 0; j < 3; ++j) { const int c = lane + 64 * j, rw = c / 12, cc = c % 12; const int row2 = 16 * (mi ? blk1 : pb) + rw, b2 = row2 / TT, t2 = row2 % TT;
;                         const u32x4 v = *(const LAS u32x4*)(stg + rw * 104 + 8 * cc);
;                         if (valid) __builtin_nontemporal_store(v, (u32x4*)(Kb + (((size_t)(b2 * NH + h)) * TKP + t2) * QKH + 8 * cc)); }
	v_add_f32_e32 v121, v121, v122
	v_mov_b32_e32 v122, v121
	s_nop 1
	v_permlane32_swap_b32_e32 v121, v122
	s_waitcnt lgkmcnt(0)
	v_add_f32_e32 v121, v121, v122
	v_fmamk_f32 v121, v121, 0x3c2aaaab, v140
	v_rsq_f32_e32 v122, v121
	s_nop 0
	v_pk_mul_f32 v[86:87], v[86:87], v[122:123] op_sel_hi:[1,0]
	v_pk_mul_f32 v[98:99], v[98:99], v[122:123] op_sel_hi:[1,0]
	v_pk_mul_f32 v[88:89], v[88:89], v[122:123] op_sel_hi:[1,0]
	v_pk_mul_f32 v[86:87], v[10:11], v[86:87]
	v_pk_mul_f32 v[100:101], v[100:101], v[122:123] op_sel_hi:[1,0]
	v_pk_mul_f32 v[98:99], v[6:7], v[98:99]
	v_pk_mul_f32 v[88:89], v[12:13], v[88:89]
	v_cvt_pk_bf16_f32 v86, v86, v87
	v_pk_mul_f32 v[100:101], v[8:9], v[100:101]
	v_cvt_pk_bf16_f32 v87, v88, v89
	v_cvt_pk_bf16_f32 v98, v98, v99
	v_pk_mul_f32 v[88:89], v[96:97], v[122:123] op_sel_hi:[1,0]
	v_cvt_pk_bf16_f32 v99, v100, v101
	ds_write2_b64 v127, v[98:99], v[86:87] offset1:4
	v_pk_mul_f32 v[86:87], v[94:95], v[122:123] op_sel_hi:[1,0]
	v_pk_mul_f32 v[88:89], v[16:17], v[88:89]
	v_pk_mul_f32 v[86:87], v[14:15], v[86:87]
	s_nop 0
	v_cvt_pk_bf16_f32 v86, v86, v87
	v_cvt_pk_bf16_f32 v87, v88, v89
	v_pk_mul_f32 v[88:89], v[90:91], v[122:123] op_sel_hi:[1,0]
	v_pk_mul_f32 v[90:91], v[92:93], v[122:123] op_sel_hi:[1,0]
	v_pk_mul_f32 v[88:89], v[18:19], v[88:89]
	v_pk_mul_f32 v[90:91], v[20:21], v[90:91]
	v_cvt_pk_bf16_f32 v88, v88, v89
	v_pk_mul_f32 v[92:93], v[136:137], v[122:123] op_sel_hi:[1,0]
	v_cvt_pk_bf16_f32 v89, v90, v91
	ds_write2_b64 v127, v[86:87], v[88:89] offset0:8 offset1:12
	v_mul_hi_i32 v86, v120, s90
	v_lshrrev_b32_e32 v87, 31, v86
	v_ashrrev_i32_e32 v86, 7, v86
	v_add_u32_e32 v86, v86, v87
	v_mul_lo_u32 v86, v86, s86
	v_sub_u32_e32 v90, v120, v86
	v_cvt_f32_i32_e32 v100, v90
	v_mov_b32_e32 v86, v133
	v_mov_b32_e32 v133, v124
	v_pk_mul_f32 v[88:89], v[122:123], v[132:133] op_sel_hi:[0,1]
	v_mul_f32_e32 v94, v154, v100
	v_mul_f32_e32 v95, 0.15915494, v94
	v_rndne_f32_e32 v95, v95
	v_fmac_f32_e32 v94, 0xc0c90fdb, v95
	v_fmac_f32_e32 v94, 0x343bbd2e, v95
	v_mul_f32_e32 v94, 0.15915494, v94
	v_sin_f32_e32 v95, v94
	v_cos_f32_e32 v94, v94
	v_mov_b32_e32 v96, v88
	v_mul_f32_e32 v88, v155, v100
	v_mov_b32_e32 v97, v92
	v_mul_f32_e32 v92, 0.15915494, v88
	v_rndne_f32_e32 v92, v92
	v_pk_mul_f32 v[96:97], v[118:119], v[96:97]
	v_fmac_f32_e32 v88, 0xc0c90fdb, v92
	v_pk_mul_f32 v[98:99], v[94:95], v[96:97]
	v_fmac_f32_e32 v88, 0x343bbd2e, v92
	v_sub_f32_e32 v101, v98, v99
	v_mov_b32_e32 v98, v95
	v_mov_b32_e32 v99, v94
	v_mul_f32_e32 v88, 0.15915494, v88
	v_pk_mul_f32 v[94:95], v[98:99], v[96:97]
	v_sin_f32_e32 v97, v88
	v_cos_f32_e32 v96, v88
	v_mov_b32_e32 v92, v89
	v_pk_mul_f32 v[88:89], v[2:3], v[92:93]
	v_mov_b32_e32 v87, v125
	v_pk_mul_f32 v[92:93], v[96:97], v[88:89]
	v_pk_mul_f32 v[86:87], v[122:123], v[86:87] op_sel_hi:[0,1]
	v_sub_f32_e32 v99, v92, v93
	v_mov_b32_e32 v92, v97
	v_mov_b32_e32 v93, v96
	v_pk_mul_f32 v[88:89], v[92:93], v[88:89]
	v_pk_mul_f32 v[90:91], v[128:129], v[122:123] op_sel_hi:[1,0]
	v_add_f32_e32 v96, v88, v89
	v_mul_f32_e32 v88, v156, v100
	v_mul_f32_e32 v89, 0.15915494, v88
	v_rndne_f32_e32 v89, v89
	v_fmac_f32_e32 v88, 0xc0c90fdb, v89
	v_fmac_f32_e32 v88, 0x343bbd2e, v89
	v_mul_f32_e32 v88, 0.15915494, v88
	v_sin_f32_e32 v89, v88
	v_cos_f32_e32 v88, v88
	v_mov_b32_e32 v92, v86
	v_mul_f32_e32 v86, v157, v100
	v_mov_b32_e32 v93, v90
	v_mul_f32_e32 v90, 0.15915494, v86
	v_rndne_f32_e32 v90, v90
	v_pk_mul_f32 v[92:93], v[116:117], v[92:93]
	v_fmac_f32_e32 v86, 0xc0c90fdb, v90
	v_add_f32_e32 v98, v94, v95
	v_pk_mul_f32 v[94:95], v[88:89], v[92:93]
	v_fmac_f32_e32 v86, 0x343bbd2e, v90
	v_sub_f32_e32 v97, v94, v95
	v_mov_b32_e32 v94, v89
	v_mov_b32_e32 v95, v88
	v_mul_f32_e32 v86, 0.15915494, v86
	v_pk_mul_f32 v[88:89], v[94:95], v[92:93]
	v_sin_f32_e32 v93, v86
	v_cos_f32_e32 v92, v86
	v_mov_b32_e32 v90, v87
	v_pk_mul_f32 v[86:87], v[4:5], v[90:91]
	v_add_f32_e32 v94, v88, v89
	v_pk_mul_f32 v[88:89], v[92:93], v[86:87]
	s_nop 0
	v_sub_f32_e32 v90, v88, v89
	v_mov_b32_e32 v88, v93
	v_mov_b32_e32 v89, v92
	v_pk_mul_f32 v[86:87], v[88:89], v[86:87]
	v_cvt_pk_bf16_f32 v88, v98, v96
	s_nop 0
	v_add_f32_e32 v89, v86, v87
	v_cvt_pk_bf16_f32 v86, v101, v99
	v_cvt_pk_bf16_f32 v87, v97, v90
	v_cvt_pk_bf16_f32 v89, v94, v89
	ds_write2_b64 v127, v[86:87], v[88:89] offset0:16 offset1:20
	s_waitcnt lgkmcnt(0)
	s_and_saveexec_b64 s[4:5], vcc
	s_cbranch_execz .LBB0_526
	v_or_b32_e32 v90, v178, v107
	v_mul_hi_i32 v91, v90, s90
	v_lshrrev_b32_e32 v92, 31, v91
	v_ashrrev_i32_e32 v91, 7, v91
	v_add_u32_e32 v91, v91, v92
	v_mul_i32_i24_e32 v92, 0x810, v91
	v_sub_u32_e32 v90, v90, v92
	v_lshl_or_b32 v91, v91, 3, s16
	v_mul_hi_i32_i24_e32 v93, 0x840, v91
	v_mul_i32_i24_e32 v92, 0x840, v91
	v_ashrrev_i32_e32 v91, 31, v90
	ds_read_b128 v[86:89], v173
	v_lshl_add_u64 v[90:91], v[92:93], 0, v[90:91]
	v_mad_u64_u32 v[94:95], s[8:9], v90, s91, v[108:109]
	v_mov_b32_e32 v90, v95
	v_mad_u64_u32 v[90:91], s[8:9], v91, s91, v[90:91]
	v_mov_b32_e32 v95, v90
	ds_read_b128 v[90:93], v174
	s_waitcnt lgkmcnt(1)
	global_store_dwordx4 v[94:95], v[86:89], off
	s_nop 1
	v_or_b32_e32 v86, v178, v170
	v_mul_hi_i32 v87, v86, s90
	v_lshrrev_b32_e32 v88, 31, v87
	v_ashrrev_i32_e32 v87, 7, v87
	v_add_u32_e32 v87, v87, v88
	v_mul_i32_i24_e32 v88, 0x810, v87
	v_sub_u32_e32 v86, v86, v88
	v_lshl_or_b32 v87, v87, 3, s16
	v_mul_hi_i32_i24_e32 v89, 0x840, v87
	v_mul_i32_i24_e32 v88, 0x840, v87
	v_ashrrev_i32_e32 v87, 31, v86
	v_lshl_add_u64 v[86:87], v[88:89], 0, v[86:87]
	v_mad_u64_u32 v[88:89], s[8:9], v86, s91, v[110:111]
	v_mov_b32_e32 v86, v89
	v_mad_u64_u32 v[86:87], s[8:9], v87, s91, v[86:87]
	v_mov_b32_e32 v89, v86
	s_waitcnt lgkmcnt(0)
	global_store_dwordx4 v[88:89], v[90:93], off
	ds_read_b128 v[86:89], v175
	s_nop 0
	v_or_b32_e32 v90, v178, v171
	v_mul_hi_i32 v91, v90, s90
	v_lshrrev_b32_e32 v92, 31, v91
	v_ashrrev_i32_e32 v91, 7, v91
	v_add_u32_e32 v91, v91, v92
	v_mul_i32_i24_e32 v92, 0x810, v91
	v_sub_u32_e32 v90, v90, v92
	v_lshl_or_b32 v91, v91, 3, s16
	v_mul_hi_i32_i24_e32 v93, 0x840, v91
	v_mul_i32_i24_e32 v92, 0x840, v91
	v_ashrrev_i32_e32 v91, 31, v90
	v_lshl_add_u64 v[90:91], v[92:93], 0, v[90:91]
	v_mad_u64_u32 v[92:93], s[8:9], v90, s91, v[112:113]
	v_mov_b32_e32 v90, v93
	v_mad_u64_u32 v[90:91], s[8:9], v91, s91, v[90:91]
	v_mov_b32_e32 v93, v90
	s_waitcnt lgkmcnt(0)
	global_store_dwordx4 v[92:93], v[86:89], off
; #define LAS __attribute__((address_space(3)))
; #define MFMA16(a, b, c) __builtin_amdgcn_mfma_f32_16x16x32_bf16((a), (b), (c), 0, 0, 0)
; __device__ __forceinline__ void qkv_head_unit(const Params& p, LAS unsigned char* lds, int h, int blk_begin, int blk_end) {
;     ...
;             {
;                 f32x4 acc[2][4];
; #pragma unroll
;                 for (int m = 0; m < 2; ++m)
; #pragma unroll
;                     for (int n = 0; n < 4; ++n) acc[m][n] = (f32x4){0.f, 0.f, 0.f, 0.f};
; #pragma unroll
;                 for (int ks = 0; ks < 8; ++ks)
; #pragma unroll
;                     for (int n = 0; n < 4; ++n) { const bf16x8 bw = *(const LAS bf16x8*)(wl + (64 + 16 * n + fr) * WKS + 32 * ks + 8 * fq);
;                         acc[0][n] = MFMA16(bw, af[0][ks], acc[0][n]); acc[1][n] = MFMA16(bw, af[1][ks], acc[1][n]); }
.LBB0_526:
	s_or_b64 exec, exec, s[4:5]
	s_waitcnt lgkmcnt(0)
	ds_read_b128 v[230:233], v165 offset:33792
	ds_read_b128 v[234:237], v165 offset:42240
	ds_read_b128 v[238:241], v165 offset:50688
	ds_read_b128 v[184:187], v165 offset:59136
	s_waitcnt lgkmcnt(3)
	v_mfma_f32_16x16x32_bf16 v[86:89], v[230:233], v[78:81], 0
	v_mfma_f32_16x16x32_bf16 v[90:93], v[230:233], v[82:85], 0
	ds_read_b128 v[230:233], v165 offset:33856
	s_waitcnt lgkmcnt(3)
	v_mfma_f32_16x16x32_bf16 v[94:97], v[234:237], v[78:81], 0
	v_mfma_f32_16x16x32_bf16 v[98:101], v[234:237], v[82:85], 0
	ds_read_b128 v[234:237], v165 offset:42304
	s_waitcnt lgkmcnt(3)
	v_mfma_f32_16x16x32_bf16 v[120:123], v[238:241], v[78:81], 0
	v_mfma_f32_16x16x32_bf16 v[128:131], v[238:241], v[82:85], 0
	ds_read_b128 v[238:241], v165 offset:50752
	s_waitcnt lgkmcnt(3)
	v_mfma_f32_16x16x32_bf16 v[132:135], v[184:187], v[78:81], 0
	v_mfma_f32_16x16x32_bf16 v[180:183], v[184:187], v[82:85], 0
	ds_read_b128 v[184:187], v165 offset:59200
	s_waitcnt lgkmcnt(3)
	v_mfma_f32_16x16x32_bf16 v[86:89], v[230:233], v[66:69], v[86:89]
	v_mfma_f32_16x16x32_bf16 v[90:93], v[230:233], v[74:77], v[90:93]
	ds_read_b128 v[230:233], v165 offset:33920
	s_waitcnt lgkmcnt(3)
	v_mfma_f32_16x16x32_bf16 v[94:97], v[234:237], v[66:69], v[94:97]
	v_mfma_f32_16x16x32_bf16 v[98:101], v[234:237], v[74:77], v[98:101]
	ds_read_b128 v[234:237], v165 offset:42368
	s_waitcnt lgkmcnt(3)
	v_mfma_f32_16x16x32_bf16 v[120:123], v[238:241], v[66:69], v[120:123]
	v_mfma_f32_16x16x32_bf16 v[128:131], v[238:241], v[74:77], v[128:131]
	ds_read_b128 v[238:241], v165 offset:50816
	s_waitcnt lgkmcnt(3)
	v_mfma_f32_16x16x32_bf16 v[132:135], v[184:187], v[66:69], v[132:135]
	v_mfma_f32_16x16x32_bf16 v[180:183], v[184:187], v[74:77], v[180:183]
	ds_read_b128 v[184:187], v165 offset:59264
	s_waitcnt lgkmcnt(3)
	v_mfma_f32_16x16x32_bf16 v[86:89], v[230:233], v[62:65], v[86:89]
	v_mfma_f32_16x16x32_bf16 v[90:93], v[230:233], v[70:73], v[90:93]
	ds_read_b128 v[230:233], v165 offset:33984
	s_waitcnt lgkmcnt(3)
	v_mfma_f32_16x16x32_bf16 v[94:97], v[234:237], v[62:65], v[94:97]
	v_mfma_f32_16x16x32_bf16 v[98:101], v[234:237], v[70:73], v[98:101]
	ds_read_b128 v[234:237], v165 offset:42432
	s_waitcnt lgkmcnt(3)
	v_mfma_f32_16x16x32_bf16 v[120:123], v[238:241], v[62:65], v[120:123]
	v_mfma_f32_16x16x32_bf16 v[128:131], v[238:241], v[70:73], v[128:131]
	ds_read_b128 v[238:241], v165 offset:50880
	s_waitcnt lgkmcnt(3)
	v_mfma_f32_16x16x32_bf16 v[132:135], v[184:187], v[62:65], v[132:135]
	v_mfma_f32_16x16x32_bf16 v[180:183], v[184:187], v[70:73], v[180:183]
	ds_read_b128 v[184:187], v165 offset:59328
	s_waitcnt lgkmcnt(3)
	v_mfma_f32_16x16x32_bf16 v[86:89], v[230:233], v[50:53], v[86:89]
	v_mfma_f32_16x16x32_bf16 v[90:93], v[230:233], v[58:61], v[90:93]
	ds_read_b128 v[230:233], v165 offset:34048
	s_waitcnt lgkmcnt(3)
	v_mfma_f32_16x16x32_bf16 v[94:97], v[234:237], v[50:53], v[94:97]
	v_mfma_f32_16x16x32_bf16 v[98:101], v[234:237], v[58:61], v[98:101]
	ds_read_b128 v[234:237], v165 offset:42496
	s_waitcnt lgkmcnt(3)
	v_mfma_f32_16x16x32_bf16 v[120:123], v[238:241], v[50:53], v[120:123]
	v_mfma_f32_16x16x32_bf16 v[128:131], v[238:241], v[58:61], v[128:131]
	ds_read_b128 v[238:241], v165 offset:50944
	s_waitcnt lgkmcnt(3)
	v_mfma_f32_16x16x32_bf16 v[132:135], v[184:187], v[50:53], v[132:135]
	v_mfma_f32_16x16x32_bf16 v[180:183], v[184:187], v[58:61], v[180:183]
	ds_read_b128 v[184:187], v165 offset:59392
	s_waitcnt lgkmcnt(3)
	v_mfma_f32_16x16x32_bf16 v[86:89], v[230:233], v[46:49], v[86:89]
	v_mfma_f32_16x16x32_bf16 v[90:93], v[230:233], v[54:57], v[90:93]
	ds_read_b128 v[230:233], v165 offset:34112
	s_waitcnt lgkmcnt(3)
	v_mfma_f32_16x16x32_bf16 v[94:97], v[234:237], v[46:49], v[94:97]
	v_mfma_f32_16x16x32_bf16 v[98:101], v[234:237], v[54:57], v[98:101]
	ds_read_b128 v[234:237], v165 offset:42560
	s_waitcnt lgkmcnt(3)
	v_mfma_f32_16x16x32_bf16 v[120:123], v[238:241], v[46:49], v[120:123]
	v_mfma_f32_16x16x32_bf16 v[128:131], v[238:241], v[54:57], v[128:131]
	ds_read_b128 v[238:241], v165 offset:51008
	s_waitcnt lgkmcnt(3)
	v_mfma_f32_16x16x32_bf16 v[132:135], v[184:187], v[46:49], v[132:135]
	v_mfma_f32_16x16x32_bf16 v[180:183], v[184:187], v[54:57], v[180:183]
	ds_read_b128 v[184:187], v165 offset:59456
	s_waitcnt lgkmcnt(3)
	v_mfma_f32_16x16x32_bf16 v[86:89], v[230:233], v[38:41], v[86:89]
	v_mfma_f32_16x16x32_bf16 v[90:93], v[230:233], v[42:45], v[90:93]
	ds_read_b128 v[230:233], v165 offset:34176
	s_waitcnt lgkmcnt(3)
	v_mfma_f32_16x16x32_bf16 v[94:97], v[234:237], v[38:41], v[94:97]
	v_mfma_f32_16x16x32_bf16 v[98:101], v[234:237], v[42:45], v[98:101]
	ds_read_b128 v[234:237], v165 offset:42624
	s_waitcnt lgkmcnt(3)
	v_mfma_f32_16x16x32_bf16 v[120:123], v[238:241], v[38:41], v[120:123]
	v_mfma_f32_16x16x32_bf16 v[128:131], v[238:241], v[42:45], v[128:131]
	ds_read_b128 v[238:241], v165 offset:51072
	s_waitcnt lgkmcnt(3)
	v_mfma_f32_16x16x32_bf16 v[132:135], v[184:187], v[38:41], v[132:135]
	v_mfma_f32_16x16x32_bf16 v[180:183], v[184:187], v[42:45], v[180:183]
	ds_read_b128 v[184:187], v165 offset:59520
	s_waitcnt lgkmcnt(3)
	v_mfma_f32_16x16x32_bf16 v[86:89], v[230:233], v[30:33], v[86:89]
	v_mfma_f32_16x16x32_bf16 v[90:93], v[230:233], v[34:37], v[90:93]
	ds_read_b128 v[230:233], v165 offset:34240
	s_waitcnt lgkmcnt(3)
	v_mfma_f32_16x16x32_bf16 v[94:97], v[234:237], v[30:33], v[94:97]
	v_mfma_f32_16x16x32_bf16 v[98:101], v[234:237], v[34:37], v[98:101]
	ds_read_b128 v[234:237], v165 offset:42688
	s_waitcnt lgkmcnt(3)
	v_mfma_f32_16x16x32_bf16 v[120:123], v[238:241], v[30:33], v[120:123]
	v_mfma_f32_16x16x32_bf16 v[128:131], v[238:241], v[34:37], v[128:131]
	ds_read_b128 v[238:241], v165 offset:51136
	s_waitcnt lgkmcnt(3)
; #define LAS __attribute__((address_space(3)))
; __device__ __forceinline__ unsigned cvt_pk(float lo, float hi) { unsigned r; asm("v_cvt_pk_bf16_f32 %0, %1, %2" : "=v"(r) : "v"(lo), "v"(hi)); return r; }
; __device__ __forceinline__ float frsq(float x) { return __builtin_amdgcn_rsqf(x); }
; #define MFMA16(a, b, c) __builtin_amdgcn_mfma_f32_16x16x32_bf16((a), (b), (c), 0, 0, 0)
; __device__ __forceinline__ void qkv_head_unit(const Params& p, LAS unsigned char* lds, int h, int blk_begin, int blk_end) {
;     ...
;             {
;                 f32x4 acc[2][4];
; #pragma unroll
;                 for (int m = 0; m < 2; ++m)
; #pragma unroll
;                     for (int n = 0; n < 4; ++n) acc[m][n] = (f32x4){0.f, 0.f, 0.f, 0.f};
; #pragma unroll
;                 for (int ks = 0; ks < 8; ++ks)
; #pragma unroll
;                     for (int n = 0; n < 4; ++n) { const bf16x8 bw = *(const LAS bf16x8*)(wl + (64 + 16 * n + fr) * WKS + 32 * ks + 8 * fq);
;                         acc[0][n] = MFMA16(bw, af[0][ks], acc[0][n]); acc[1][n] = MFMA16(bw, af[1][ks], acc[1][n]); }
; #pragma unroll
;                 for (int mi = 0; mi < 2; ++mi) {
;                     const bool valid = (mi == 0) || two;
;                     const float sc = frsq(ssv[mi] * (1.0f / 256.0f) + EPS);
; #pragma unroll
;                     for (int n = 0; n < 4; ++n)
; #pragma unroll
;                         for (int i = 0; i < 4; ++i) { const int d = 16 * n + 4 * fq + i; stg[d * 16 + fr] = (bf16_t)(cvt_pk(acc[mi][n][i] * sc, 0.f) & 0xffffu); }
;                     asm volatile("s_waitcnt lgkmcnt(0)" ::: "memory");
;                     { const int row2 = 16 * (mi ? blk1 : pb), b2 = row2 / TT, t2 = row2 % TT;
;                       bf16_t* dstv = Vt + (((size_t)(b2 * NH + h)) * NKT + (t2 >> 6)) * 4096 + (t2 & 63);
; #pragma unroll
;                       for (int j = 0; j < 2; ++j) { const int c = lane + 64 * j, d = c >> 1, hf = c & 1; if (valid) __builtin_nontemporal_store(*(const LAS u32x4*)(stg + d * 16 + 8 * hf), (u32x4*)(dstv + d * 64 + 8 * hf)); } }
;                     asm volatile("s_waitcnt lgkmcnt(0)" ::: "memory"); __builtin_amdgcn_sched_barrier(0);
	v_mfma_f32_16x16x32_bf16 v[132:135], v[184:187], v[30:33], v[132:135]
	v_mfma_f32_16x16x32_bf16 v[180:183], v[184:187], v[34:37], v[180:183]
	ds_read_b128 v[184:187], v165 offset:59584
	s_waitcnt lgkmcnt(3)
	v_mfma_f32_16x16x32_bf16 v[50:53], v[230:233], v[22:25], v[86:89]
	v_mfma_f32_16x16x32_bf16 v[30:33], v[230:233], v[26:29], v[90:93]
	s_waitcnt lgkmcnt(2)
	v_mfma_f32_16x16x32_bf16 v[46:49], v[234:237], v[22:25], v[94:97]
	v_mfma_f32_16x16x32_bf16 v[34:37], v[234:237], v[26:29], v[98:101]
	s_waitcnt lgkmcnt(1)
	v_mfma_f32_16x16x32_bf16 v[54:57], v[238:241], v[22:25], v[120:123]
	v_mfma_f32_16x16x32_bf16 v[38:41], v[238:241], v[26:29], v[128:131]
	s_waitcnt lgkmcnt(0)
	v_mfma_f32_16x16x32_bf16 v[62:65], v[184:187], v[22:25], v[132:135]
	v_mfma_f32_16x16x32_bf16 v[22:25], v[184:187], v[26:29], v[180:183]
	s_nop 7
	v_mul_f32_e32 v26, v0, v50
	v_cvt_pk_bf16_f32 v26, v26, v1
	ds_write_b16 v166, v26
	v_mul_f32_e32 v26, v0, v51
	v_cvt_pk_bf16_f32 v26, v26, v1
	ds_write_b16 v167, v26
	v_mul_f32_e32 v26, v0, v52
	v_cvt_pk_bf16_f32 v26, v26, v1
	ds_write_b16 v168, v26
	v_mul_f32_e32 v26, v0, v53
	v_cvt_pk_bf16_f32 v26, v26, v1
	ds_write_b16 v169, v26
	v_mul_f32_e32 v26, v0, v46
	v_cvt_pk_bf16_f32 v26, v26, v1
	ds_write_b16 v166, v26 offset:512
	v_mul_f32_e32 v26, v0, v47
	v_cvt_pk_bf16_f32 v26, v26, v1
	ds_write_b16 v166, v26 offset:544
	v_mul_f32_e32 v26, v0, v48
	v_cvt_pk_bf16_f32 v26, v26, v1
	ds_write_b16 v166, v26 offset:576
	v_mul_f32_e32 v26, v0, v49
	v_cvt_pk_bf16_f32 v26, v26, v1
	ds_write_b16 v166, v26 offset:608
	v_mul_f32_e32 v26, v0, v54
	v_cvt_pk_bf16_f32 v26, v26, v1
	ds_write_b16 v166, v26 offset:1024
	v_mul_f32_e32 v26, v0, v55
	v_cvt_pk_bf16_f32 v26, v26, v1
	ds_write_b16 v166, v26 offset:1056
	v_mul_f32_e32 v26, v0, v56
	v_cvt_pk_bf16_f32 v26, v26, v1
	ds_write_b16 v166, v26 offset:1088
	v_mul_f32_e32 v26, v0, v57
	v_cvt_pk_bf16_f32 v26, v26, v1
	ds_write_b16 v166, v26 offset:1120
	v_mul_f32_e32 v26, v0, v62
	v_cvt_pk_bf16_f32 v26, v26, v1
	ds_write_b16 v166, v26 offset:1536
	v_mul_f32_e32 v26, v0, v63
	v_cvt_pk_bf16_f32 v26, v26, v1
	ds_write_b16 v166, v26 offset:1568
	v_mul_f32_e32 v26, v0, v64
	v_mul_f32_e32 v0, v0, v65
	v_cvt_pk_bf16_f32 v0, v0, v1
	v_cvt_pk_bf16_f32 v26, v26, v1
	ds_write_b16 v166, v0 offset:1632
	v_mul_hi_i32 v0, v159, s90
	ds_write_b16 v166, v26 offset:1600
	v_lshrrev_b32_e32 v26, 31, v0
	v_lshrrev_b32_e32 v0, 3, v0
	v_add_u32_e32 v0, v0, v26
	v_mul_hi_i32 v26, v161, s90
	v_lshrrev_b32_e32 v27, 31, v26
	v_ashrrev_i32_e32 v26, 7, v26
	v_add_u32_e32 v26, v26, v27
	v_mul_lo_u32 v26, v26, s86
	v_sub_u32_e32 v28, v161, v26
	v_ashrrev_i32_e32 v26, 6, v28
	v_lshl_or_b32 v0, v0, 3, s16
	v_ashrrev_i32_e32 v27, 31, v26
	s_waitcnt lgkmcnt(0)
	v_mad_i64_i32 v[26:27], s[4:5], v0, 33, v[26:27]
	v_lshlrev_b64 v[26:27], 13, v[26:27]
	v_and_b32_e32 v0, 48, v28
	ds_read_b128 v[42:45], v172
	v_lshl_add_u64 v[26:27], s[46:47], 0, v[26:27]
	v_lshlrev_b32_e32 v0, 1, v0
	v_lshl_add_u64 v[26:27], v[26:27], 0, v[0:1]
	v_lshlrev_b32_e32 v0, 1, v102
	v_lshl_add_u64 v[46:47], v[26:27], 0, v[0:1]
	v_lshlrev_b32_e32 v28, 1, v104
	v_mov_b32_e32 v29, v1
	v_lshl_add_u64 v[26:27], v[46:47], 0, v[28:29]
	s_waitcnt lgkmcnt(0)
	global_store_dwordx4 v[26:27], v[42:45], off
	ds_read_b128 v[42:45], v176
	v_lshlrev_b32_e32 v26, 1, v106
	v_mov_b32_e32 v27, v1
	v_lshl_add_u64 v[46:47], v[46:47], 0, v[26:27]
	s_waitcnt lgkmcnt(0)
	global_store_dwordx4 v[46:47], v[42:45], off
	s_waitcnt lgkmcnt(0)
	v_mul_f32_e32 v30, v126, v30
	v_cvt_pk_bf16_f32 v30, v30, v1
	ds_write_b16 v166, v30
	v_mul_f32_e32 v30, v126, v31
	v_cvt_pk_bf16_f32 v30, v30, v1
	ds_write_b16 v167, v30
	v_mul_f32_e32 v30, v126, v32
	v_cvt_pk_bf16_f32 v30, v30, v1
	ds_write_b16 v168, v30
	v_mul_f32_e32 v30, v126, v33
	v_cvt_pk_bf16_f32 v30, v30, v1
	ds_write_b16 v169, v30
	v_mul_f32_e32 v30, v126, v34
	v_cvt_pk_bf16_f32 v30, v30, v1
	ds_write_b16 v166, v30 offset:512
	v_mul_f32_e32 v30, v126, v35
	v_cvt_pk_bf16_f32 v30, v30, v1
	ds_write_b16 v166, v30 offset:544
	v_mul_f32_e32 v30, v126, v36
	v_cvt_pk_bf16_f32 v30, v30, v1
	ds_write_b16 v166, v30 offset:576
	v_mul_f32_e32 v30, v126, v37
	v_cvt_pk_bf16_f32 v30, v30, v1
	ds_write_b16 v166, v30 offset:608
	v_mul_f32_e32 v30, v126, v38
	v_mul_f32_e32 v22, v126, v22
	v_cvt_pk_bf16_f32 v30, v30, v1
	v_cvt_pk_bf16_f32 v22, v22, v1
	ds_write_b16 v166, v30 offset:1024
	v_mul_f32_e32 v30, v126, v39
	ds_write_b16 v166, v22 offset:1536
	v_mul_f32_e32 v22, v126, v23
	v_cvt_pk_bf16_f32 v30, v30, v1
	v_cvt_pk_bf16_f32 v22, v22, v1
	ds_write_b16 v166, v30 offset:1056
	v_mul_f32_e32 v30, v126, v40
	ds_write_b16 v166, v22 offset:1568
	v_mul_f32_e32 v22, v126, v24
	v_cvt_pk_bf16_f32 v30, v30, v1
	v_cvt_pk_bf16_f32 v22, v22, v1
	ds_write_b16 v166, v30 offset:1088
	v_mul_f32_e32 v30, v126, v41
	ds_write_b16 v166, v22 offset:1600
	v_mul_f32_e32 v22, v126, v25
	v_cvt_pk_bf16_f32 v30, v30, v1
	ds_write_b16 v166, v30 offset:1120
	v_cvt_pk_bf16_f32 v22, v22, v1
	ds_write_b16 v166, v22 offset:1632
	s_waitcnt lgkmcnt(0)
	s_and_saveexec_b64 s[4:5], vcc
	s_cbranch_execz .LBB0_523
	v_mul_hi_i32 v22, v177, s90
	v_lshrrev_b32_e32 v23, 31, v22
	v_lshrrev_b32_e32 v22, 3, v22
	v_add_u32_e32 v22, v22, v23
	v_lshl_or_b32 v24, v22, 3, s16
	v_mul_hi_i32 v22, v178, s90
	v_lshrrev_b32_e32 v23, 31, v22
	v_ashrrev_i32_e32 v22, 7, v22
	v_add_u32_e32 v22, v22, v23
	v_mul_lo_u32 v22, v22, s86
	v_sub_u32_e32 v25, v178, v22
	v_ashrrev_i32_e32 v22, 6, v25
	v_ashrrev_i32_e32 v23, 31, v22
	v_mad_i64_i32 v[22:23], s[8:9], v24, 33, v[22:23]
	v_lshlrev_b64 v[22:23], 13, v[22:23]
	v_and_b32_e32 v24, 48, v25
	v_lshl_add_u64 v[22:23], s[46:47], 0, v[22:23]
	v_lshlrev_b32_e32 v24, 1, v24
	v_mov_b32_e32 v25, v1
	v_lshl_add_u64 v[22:23], v[22:23], 0, v[24:25]
	v_lshl_add_u64 v[30:31], v[22:23], 0, v[0:1]
	ds_read_b128 v[22:25], v172
	v_lshl_add_u64 v[28:29], v[30:31], 0, v[28:29]
	v_lshl_add_u64 v[26:27], v[30:31], 0, v[26:27]
	s_waitcnt lgkmcnt(0)
	global_store_dwordx4 v[28:29], v[22:25], off
	ds_read_b128 v[22:25], v176
	s_waitcnt lgkmcnt(0)
	global_store_dwordx4 v[26:27], v[22:25], off
	s_branch .LBB0_523
